# gdn_fix loop software-pipelined: next iteration's two loads issued one iteration ahead, counted vmcnt(1)
# speedup vs baseline: 1.0011x; 1.0011x over previous
; DI unsigned pack2(float lo, float hi) { f32x2 v = {lo, hi}; bf2_t b = __builtin_convertvector(v, bf2_t); return __builtin_bit_cast(unsigned, b); }
; DI void unpack8(const u32x4& v, float* f) { f[0] = bflo(v.x); f[1] = bfhi(v.x); f[2] = bflo(v.y); f[3] = bfhi(v.y); f[4] = bflo(v.z); f[5] = bfhi(v.z); f[6] = bflo(v.w); f[7] = bfhi(v.w); }
; DI float row16_sum(float v) { v += dppf<0xB1>(v); v += dppf<0x4E>(v); v += dppf<0x141>(v); v += dppf<0x140>(v); return v; }
; DI void gdn_fix_phase(const Params& P) {
;     ...
;   for (int idx = blockIdx.x * NT + tid; idx < S_ * 128; idx += gridDim.x * NT) {
;     const int t = idx >> 7, ck = idx & 127, h = ck >> 4;
;     const int p = (tid & 15) >> 1;
;     float sq = ((tid & 1) == 0) ? ssqp[((size_t)p * S_ + t) * 8 + h] : 0.f;
;     sq = row16_sum(sq);
;     const float r = rsqrtf(sq * (1.f / 128.f) + EPS);
;     u32x4* pp = (u32x4*)(mixin + (size_t)t * 2048 + ck * 8); const u32x4 v = *pp; float f[8]; unpack8(v, f);
;     u32x4 o = {pack2(f[0] * r, f[1] * r), pack2(f[2] * r, f[3] * r), pack2(f[4] * r, f[5] * r), pack2(f[6] * r, f[7] * r)}; *pp = o;
;   }
.LBB0_753:
	s_or_b64 exec, exec, s[0:1]
	v_mov_b32_e32 v0, v206
	v_readlane_b32 s0, v254, 59
	s_waitcnt lgkmcnt(0)
	s_barrier
	s_nop 0
	v_add_u32_e32 v8, s0, v0
	s_mov_b32 s0, 0x200000
	v_cmp_gt_i32_e32 vcc, s0, v8
	s_and_saveexec_b64 s[0:1], vcc
	s_cbranch_execz .LBB0_758
	global_load_dwordx2 v[2:3], v1, s[40:41] offset:1224
	v_and_b32_e32 v4, 1, v0
	v_lshrrev_b32_e32 v10, 2, v0
	v_lshlrev_b32_e32 v6, 13, v0
	v_and_b32_e32 v9, 0x7f, v0
	v_mov_b32_e32 v5, v1
	v_cmp_eq_u32_e32 vcc, 0, v4
	v_and_b32_e32 v4, 28, v10
	v_mov_b32_e32 v7, v1
	v_and_b32_e32 v0, 0x1c000, v6
	v_lshlrev_b32_e32 v6, 4, v9
	s_mov_b64 s[2:3], 0x263ea000
	s_mov_b64 s[4:5], 0
	s_waitcnt vmcnt(0)
	v_lshl_add_u64 v[4:5], v[2:3], 0, v[4:5]
	v_lshl_add_u64 v[6:7], v[2:3], 0, v[6:7]
	v_lshl_add_u64 v[2:3], v[4:5], 0, s[2:3]
	s_mov_b64 s[2:3], 0x62e8000
	v_lshl_add_u64 v[4:5], v[6:7], 0, s[2:3]
	v_ashrrev_i32_e32 v32, 7, v8
	v_ashrrev_i32_e32 v33, 31, v32
	v_lshlrev_b64 v[18:19], 12, v[32:33]
	v_lshl_add_u64 v[18:19], v[4:5], 0, v[18:19]
	global_load_dwordx4 v[26:29], v[18:19], off
	v_lshl_add_u64 v[20:21], v[32:33], 0, v[0:1]
	v_lshlrev_b64 v[20:21], 5, v[20:21]
	v_lshl_add_u64 v[20:21], v[2:3], 0, v[20:21]
	global_load_dword v30, v[20:21], off
	v_readlane_b32 s12, v254, 60
	s_waitcnt vmcnt(0)
	s_branch .LBB0_756
.LBB0_755:
	s_or_b64 exec, exec, s[2:3]
	s_waitcnt lgkmcnt(0)
	v_add_f32_dpp v9, v9, v9 quad_perm:[1,0,3,2] row_mask:0xf bank_mask:0xf bound_ctrl:1
	v_lshlrev_b64 v[6:7], 12, v[6:7]
	v_lshl_add_u64 v[6:7], v[4:5], 0, v[6:7]
	v_add_f32_dpp v9, v9, v9 quad_perm:[2,3,0,1] row_mask:0xf bank_mask:0xf bound_ctrl:1
	s_nop 1
	v_add_f32_dpp v9, v9, v9 row_half_mirror row_mask:0xf bank_mask:0xf bound_ctrl:1
	s_nop 1
	v_add_f32_dpp v9, v9, v9 row_mirror row_mask:0xf bank_mask:0xf bound_ctrl:1
	v_fmamk_f32 v9, v9, 0x3c000000, v245
	v_cmp_gt_f32_e64 s[2:3], s84, v9
	v_mul_f32_e32 v10, 0x4b800000, v9
	s_nop 0
	v_cndmask_b32_e64 v9, v9, v10, s[2:3]
	v_rsq_f32_e32 v9, v9
	s_nop 0
	v_mul_f32_e32 v10, 0x45800000, v9
	v_cndmask_b32_e64 v14, v9, v10, s[2:3]
	v_readlane_b32 s2, v254, 60
	v_lshlrev_b32_e32 v16, 16, v22
	v_and_b32_e32 v17, 0xffff0000, v22
	v_pk_mul_f32 v[16:17], v[14:15], v[16:17] op_sel_hi:[0,1]
	v_cvt_pk_bf16_f32 v10, v16, v17
	v_lshlrev_b32_e32 v16, 16, v23
	v_and_b32_e32 v17, 0xffff0000, v23
	v_pk_mul_f32 v[16:17], v[14:15], v[16:17] op_sel_hi:[0,1]
	v_cvt_pk_bf16_f32 v11, v16, v17
	v_lshlrev_b32_e32 v16, 16, v24
	v_and_b32_e32 v17, 0xffff0000, v24
	v_pk_mul_f32 v[16:17], v[14:15], v[16:17] op_sel_hi:[0,1]
	v_cvt_pk_bf16_f32 v12, v16, v17
	v_lshlrev_b32_e32 v16, 16, v25
	v_and_b32_e32 v17, 0xffff0000, v25
	v_add_u32_e32 v8, s2, v8
	s_mov_b32 s2, 0x1fffff
	v_pk_mul_f32 v[14:15], v[14:15], v[16:17] op_sel_hi:[0,1]
	v_cmp_lt_i32_e64 s[2:3], s2, v8
	v_cvt_pk_bf16_f32 v13, v14, v15
	s_or_b64 s[4:5], s[2:3], s[4:5]
	global_store_dwordx4 v[6:7], v[10:13], off
	s_andn2_b64 exec, exec, s[4:5]
	s_cbranch_execz .LBB0_758
.LBB0_756:
	v_ashrrev_i32_e32 v6, 7, v8
	v_ashrrev_i32_e32 v7, 31, v6
	s_waitcnt vmcnt(1)
	v_mov_b64_e32 v[22:23], v[26:27]
	v_mov_b64_e32 v[24:25], v[28:29]
	v_cndmask_b32_e32 v9, 0, v30, vcc
	v_add_u32_e32 v31, s12, v8
	v_ashrrev_i32_e32 v32, 7, v31
	v_ashrrev_i32_e32 v33, 31, v32
	v_lshlrev_b64 v[18:19], 12, v[32:33]
	v_lshl_add_u64 v[18:19], v[4:5], 0, v[18:19]
	global_load_dwordx4 v[26:29], v[18:19], off
	s_and_saveexec_b64 s[2:3], vcc
	s_cbranch_execz .LBB0_755
	v_lshl_add_u64 v[20:21], v[32:33], 0, v[0:1]
	v_lshlrev_b64 v[20:21], 5, v[20:21]
	v_lshl_add_u64 v[20:21], v[2:3], 0, v[20:21]
	global_load_dword v30, v[20:21], off
	s_branch .LBB0_755
